# RESID epilogues: drop 9 vmcnt(0) waits that only waited on store acks (loads already waited on every path)
# speedup vs baseline: 1.0095x; 1.0020x over previous
; template <int EPI>
; DEVI void phase_gemm(const Params& p, const bf16* A, int lda, const bf16* Bt, int K, int NT, bf16* dst, int ldd, char* smem, bool nostore = false,
;                      const float* lng = nullptr, const float* lnb = nullptr) {
;     ...
;       for (int m = 0; m < 4; ++m) {
;         const int row = mt * 128 + wr * 64 + m * 16 + fr;
;         float* rp = x + (long)row * 1024 + cb0;
;         float mu = 0.f, rstd = 1.f;
;         if (lng) { mu = stats[row * 2]; rstd = stats[row * 2 + 1]; }
;         f32x4 v[4];
; #pragma unroll
;         for (int n = 0; n < 4; ++n) v[n] = *(const f32x4*)(rp + n * 16);
; #pragma unroll
;         for (int n = 0; n < 4; ++n) {
;           f32x4 xv = v[n];
;           if (lng) xv = (xv - mu) * rstd * gv[n] + bv[n];
;           *(f32x4*)(rp + n * 16) = xv * DN_ALPHA + acc[m][n];
.LBB0_1496:
	v_pk_fma_f32 v[84:85], v[120:121], s[4:5], v[84:85] op_sel_hi:[1,0,1]
	v_pk_fma_f32 v[82:83], v[118:119], s[4:5], v[82:83] op_sel_hi:[1,0,1]
	v_pk_fma_f32 v[88:89], v[116:117], s[4:5], v[88:89] op_sel_hi:[1,0,1]
	v_pk_fma_f32 v[86:87], v[114:115], s[4:5], v[86:87] op_sel_hi:[1,0,1]
	global_store_dwordx4 v[130:131], v[82:85], off offset:192
	s_and_b64 vcc, exec, s[36:37]
	global_store_dwordx4 v[130:131], v[86:89], off offset:128
	v_or_b32_e32 v82, 16, v128
	s_cbranch_vccnz .LBB0_1499
	v_lshlrev_b32_e32 v84, 1, v82
	v_ashrrev_i32_e32 v85, 31, v84
	v_lshl_add_u64 v[84:85], v[84:85], 2, s[86:87]
	global_load_dwordx2 v[102:103], v[84:85], off
	s_branch .LBB0_1500

; template <int EPI>
; DEVI void phase_gemm(const Params& p, const bf16* A, int lda, const bf16* Bt, int K, int NT, bf16* dst, int ldd, char* smem, bool nostore = false,
;                      const float* lng = nullptr, const float* lnb = nullptr) {
;     ...
;       for (int m = 0; m < 4; ++m) {
;         const int row = mt * 128 + wr * 64 + m * 16 + fr;
;         float* rp = x + (long)row * 1024 + cb0;
;         float mu = 0.f, rstd = 1.f;
;         if (lng) { mu = stats[row * 2]; rstd = stats[row * 2 + 1]; }
;         f32x4 v[4];
; #pragma unroll
;         for (int n = 0; n < 4; ++n) v[n] = *(const f32x4*)(rp + n * 16);
; #pragma unroll
;         for (int n = 0; n < 4; ++n) {
;           f32x4 xv = v[n];
;           if (lng) xv = (xv - mu) * rstd * gv[n] + bv[n];
;           *(f32x4*)(rp + n * 16) = xv * DN_ALPHA + acc[m][n];
.LBB0_1503:
	v_pk_fma_f32 v[68:69], v[104:105], s[4:5], v[68:69] op_sel_hi:[1,0,1]
	v_pk_fma_f32 v[66:67], v[102:103], s[4:5], v[66:67] op_sel_hi:[1,0,1]
	v_pk_fma_f32 v[72:73], v[100:101], s[4:5], v[72:73] op_sel_hi:[1,0,1]
	v_pk_fma_f32 v[70:71], v[98:99], s[4:5], v[70:71] op_sel_hi:[1,0,1]
	global_store_dwordx4 v[106:107], v[66:69], off offset:192
	s_and_b64 vcc, exec, s[36:37]
	global_store_dwordx4 v[106:107], v[70:73], off offset:128
	v_or_b32_e32 v66, 32, v128
	s_cbranch_vccnz .LBB0_1506
	v_lshlrev_b32_e32 v68, 1, v66
	v_ashrrev_i32_e32 v69, 31, v68
	v_lshl_add_u64 v[68:69], v[68:69], 2, s[86:87]
	global_load_dwordx2 v[86:87], v[68:69], off
	s_branch .LBB0_1507

; template <int EPI>
; DEVI void phase_gemm(const Params& p, const bf16* A, int lda, const bf16* Bt, int K, int NT, bf16* dst, int ldd, char* smem, bool nostore = false,
;                      const float* lng = nullptr, const float* lnb = nullptr) {
;     ...
;       for (int m = 0; m < 4; ++m) {
;         const int row = mt * 128 + wr * 64 + m * 16 + fr;
;         float* rp = x + (long)row * 1024 + cb0;
;         float mu = 0.f, rstd = 1.f;
;         if (lng) { mu = stats[row * 2]; rstd = stats[row * 2 + 1]; }
;         f32x4 v[4];
; #pragma unroll
;         for (int n = 0; n < 4; ++n) v[n] = *(const f32x4*)(rp + n * 16);
; #pragma unroll
;         for (int n = 0; n < 4; ++n) {
;           f32x4 xv = v[n];
;           if (lng) xv = (xv - mu) * rstd * gv[n] + bv[n];
;           *(f32x4*)(rp + n * 16) = xv * DN_ALPHA + acc[m][n];
.LBB0_1510:
	v_pk_fma_f32 v[52:53], v[88:89], s[4:5], v[52:53] op_sel_hi:[1,0,1]
	v_pk_fma_f32 v[50:51], v[86:87], s[4:5], v[50:51] op_sel_hi:[1,0,1]
	v_pk_fma_f32 v[56:57], v[84:85], s[4:5], v[56:57] op_sel_hi:[1,0,1]
	v_pk_fma_f32 v[54:55], v[82:83], s[4:5], v[54:55] op_sel_hi:[1,0,1]
	global_store_dwordx4 v[90:91], v[50:53], off offset:192
	s_and_b64 vcc, exec, s[36:37]
	global_store_dwordx4 v[90:91], v[54:57], off offset:128
	v_or_b32_e32 v50, 48, v128
	s_cbranch_vccnz .LBB0_1513
	v_lshlrev_b32_e32 v52, 1, v50
	v_ashrrev_i32_e32 v53, 31, v52
	v_lshl_add_u64 v[52:53], v[52:53], 2, s[86:87]
	global_load_dwordx2 v[70:71], v[52:53], off
	s_branch .LBB0_1514
